# accumulator zero-init in the three GEMM unit headers with v_mov_b64 pairs
# speedup vs baseline: 1.0055x; 1.0055x over previous
.LBB0_103:
	s_ashr_i32 s23, s22, 31
	s_lshl_b64 s[2:3], s[22:23], 19
	s_add_u32 s58, s90, s2
	s_addc_u32 s59, s77, s3
	s_and_b64 s[2:3], s[46:47], exec
	s_cselect_b32 s1, s59, s49
	s_cselect_b32 s23, s58, s48
	s_add_u32 s34, s34, 0x3e080
	s_addc_u32 s35, s35, 0
	s_add_u32 s51, s48, 0x100
	v_mov_b32_e32 v2, 0
	s_addc_u32 s52, s49, 0
	s_mov_b32 s53, -2
	v_mov_b32_e32 v3, v2
	v_mov_b64_e32 v[4:5], v[2:3]
	v_mov_b64_e32 v[6:7], v[2:3]
	v_mov_b64_e32 v[8:9], v[2:3]
	v_mov_b64_e32 v[10:11], v[2:3]
	v_mov_b64_e32 v[12:13], v[2:3]
	v_mov_b64_e32 v[14:15], v[2:3]
	v_mov_b64_e32 v[16:17], v[2:3]
	v_mov_b64_e32 v[18:19], v[2:3]
	v_mov_b64_e32 v[20:21], v[2:3]
	v_mov_b64_e32 v[22:23], v[2:3]
	v_mov_b64_e32 v[24:25], v[2:3]
	v_mov_b64_e32 v[26:27], v[2:3]
	v_mov_b64_e32 v[28:29], v[2:3]
	v_mov_b64_e32 v[30:31], v[2:3]
	v_mov_b64_e32 v[32:33], v[2:3]
	v_mov_b64_e32 v[66:67], v[2:3]
	v_mov_b64_e32 v[68:69], v[2:3]
	v_mov_b64_e32 v[70:71], v[2:3]
	v_mov_b64_e32 v[72:73], v[2:3]
	v_mov_b64_e32 v[74:75], v[2:3]
	v_mov_b64_e32 v[76:77], v[2:3]
	v_mov_b64_e32 v[78:79], v[2:3]
	v_mov_b64_e32 v[80:81], v[2:3]
	v_mov_b64_e32 v[82:83], v[2:3]
	v_mov_b64_e32 v[84:85], v[2:3]
	v_mov_b64_e32 v[86:87], v[2:3]
	v_mov_b64_e32 v[88:89], v[2:3]
	v_mov_b64_e32 v[90:91], v[2:3]
	v_mov_b64_e32 v[92:93], v[2:3]
	v_mov_b64_e32 v[94:95], v[2:3]
	v_mov_b64_e32 v[96:97], v[2:3]
	v_mov_b64_e32 v[34:35], v[2:3]
	v_mov_b64_e32 v[36:37], v[2:3]
	v_mov_b64_e32 v[38:39], v[2:3]
	v_mov_b64_e32 v[40:41], v[2:3]
	v_mov_b64_e32 v[42:43], v[2:3]
	v_mov_b64_e32 v[44:45], v[2:3]
	v_mov_b64_e32 v[46:47], v[2:3]
	v_mov_b64_e32 v[48:49], v[2:3]
	v_mov_b64_e32 v[50:51], v[2:3]
	v_mov_b64_e32 v[52:53], v[2:3]
	v_mov_b64_e32 v[54:55], v[2:3]
	v_mov_b64_e32 v[56:57], v[2:3]
	v_mov_b64_e32 v[58:59], v[2:3]
	v_mov_b64_e32 v[60:61], v[2:3]
	v_mov_b64_e32 v[62:63], v[2:3]
	v_mov_b64_e32 v[64:65], v[2:3]
	v_mov_b64_e32 v[130:131], v[2:3]
	v_mov_b64_e32 v[132:133], v[2:3]
	v_mov_b64_e32 v[134:135], v[2:3]
	v_mov_b64_e32 v[136:137], v[2:3]
	v_mov_b64_e32 v[138:139], v[2:3]
	v_mov_b64_e32 v[140:141], v[2:3]
	v_mov_b64_e32 v[142:143], v[2:3]
	v_mov_b64_e32 v[144:145], v[2:3]
	v_mov_b64_e32 v[146:147], v[2:3]
	v_mov_b64_e32 v[148:149], v[2:3]
	v_mov_b64_e32 v[150:151], v[2:3]
	v_mov_b64_e32 v[152:153], v[2:3]
	v_mov_b64_e32 v[154:155], v[2:3]
	v_mov_b64_e32 v[156:157], v[2:3]
	v_mov_b64_e32 v[158:159], v[2:3]
	v_mov_b64_e32 v[160:161], v[2:3]

.LBB0_181:
	s_add_i32 s88, s44, -2
	s_add_u32 s34, s34, 0x80
	s_addc_u32 s35, s35, 0
	s_add_u32 s89, s42, 0x100
	v_mov_b32_e32 v2, 0
	s_addc_u32 s90, s43, 0
	s_mov_b32 s2, 0
	v_mov_b32_e32 v3, v2
	v_mov_b64_e32 v[4:5], v[2:3]
	v_mov_b64_e32 v[6:7], v[2:3]
	v_mov_b64_e32 v[8:9], v[2:3]
	v_mov_b64_e32 v[10:11], v[2:3]
	v_mov_b64_e32 v[12:13], v[2:3]
	v_mov_b64_e32 v[14:15], v[2:3]
	v_mov_b64_e32 v[16:17], v[2:3]
	v_mov_b64_e32 v[18:19], v[2:3]
	v_mov_b64_e32 v[20:21], v[2:3]
	v_mov_b64_e32 v[22:23], v[2:3]
	v_mov_b64_e32 v[24:25], v[2:3]
	v_mov_b64_e32 v[26:27], v[2:3]
	v_mov_b64_e32 v[28:29], v[2:3]
	v_mov_b64_e32 v[30:31], v[2:3]
	v_mov_b64_e32 v[32:33], v[2:3]
	v_mov_b64_e32 v[66:67], v[2:3]
	v_mov_b64_e32 v[68:69], v[2:3]
	v_mov_b64_e32 v[70:71], v[2:3]
	v_mov_b64_e32 v[72:73], v[2:3]
	v_mov_b64_e32 v[74:75], v[2:3]
	v_mov_b64_e32 v[76:77], v[2:3]
	v_mov_b64_e32 v[78:79], v[2:3]
	v_mov_b64_e32 v[80:81], v[2:3]
	v_mov_b64_e32 v[82:83], v[2:3]
	v_mov_b64_e32 v[84:85], v[2:3]
	v_mov_b64_e32 v[86:87], v[2:3]
	v_mov_b64_e32 v[88:89], v[2:3]
	v_mov_b64_e32 v[90:91], v[2:3]
	v_mov_b64_e32 v[92:93], v[2:3]
	v_mov_b64_e32 v[94:95], v[2:3]
	v_mov_b64_e32 v[96:97], v[2:3]
	v_mov_b64_e32 v[34:35], v[2:3]
	v_mov_b64_e32 v[36:37], v[2:3]
	v_mov_b64_e32 v[38:39], v[2:3]
	v_mov_b64_e32 v[40:41], v[2:3]
	v_mov_b64_e32 v[42:43], v[2:3]
	v_mov_b64_e32 v[44:45], v[2:3]
	v_mov_b64_e32 v[46:47], v[2:3]
	v_mov_b64_e32 v[48:49], v[2:3]
	v_mov_b64_e32 v[50:51], v[2:3]
	v_mov_b64_e32 v[52:53], v[2:3]
	v_mov_b64_e32 v[54:55], v[2:3]
	v_mov_b64_e32 v[56:57], v[2:3]
	v_mov_b64_e32 v[58:59], v[2:3]
	v_mov_b64_e32 v[60:61], v[2:3]
	v_mov_b64_e32 v[62:63], v[2:3]
	v_mov_b64_e32 v[64:65], v[2:3]
	v_mov_b64_e32 v[98:99], v[2:3]
	v_mov_b64_e32 v[100:101], v[2:3]
	v_mov_b64_e32 v[102:103], v[2:3]
	v_mov_b64_e32 v[104:105], v[2:3]
	v_mov_b64_e32 v[106:107], v[2:3]
	v_mov_b64_e32 v[108:109], v[2:3]
	v_mov_b64_e32 v[110:111], v[2:3]
	v_mov_b64_e32 v[112:113], v[2:3]
	v_mov_b64_e32 v[114:115], v[2:3]
	v_mov_b64_e32 v[116:117], v[2:3]
	v_mov_b64_e32 v[118:119], v[2:3]
	v_mov_b64_e32 v[120:121], v[2:3]
	v_mov_b64_e32 v[122:123], v[2:3]
	v_mov_b64_e32 v[124:125], v[2:3]
	v_mov_b64_e32 v[126:127], v[2:3]
	v_mov_b64_e32 v[128:129], v[2:3]

.LBB0_365:
	v_mov_b64_e32 v[2:3], 0x30c
	v_cmp_lt_i64_e32 vcc, s[2:3], v[2:3]
	s_lshl_b32 s2, s18, 8
	s_or_b32 s2, s2, 1
	s_cmp_lt_i32 s18, 64
	s_cselect_b32 s2, s2, 0x4003
	s_ashr_i32 s3, s2, 31
	s_lshl_b64 s[2:3], s[2:3], 11
	v_readlane_b32 s12, v252, 20
	v_readlane_b32 s13, v252, 21
	s_add_u32 s52, s12, s2
	s_addc_u32 s53, s13, s3
	s_and_b64 s[2:3], vcc, exec
	s_cselect_b32 s15, s53, s1
	s_cselect_b32 s19, s52, s0
	s_ashr_i32 s51, s50, 31
	s_lshl_b64 s[2:3], s[50:51], 19
	s_add_u32 s48, s23, s2
	s_addc_u32 s49, s34, s3
	s_and_b64 s[2:3], vcc, exec
	s_cselect_b32 s43, s49, s17
	s_cselect_b32 s44, s48, s16
	s_add_u32 s0, s0, 0x40080
	s_addc_u32 s1, s1, 0
	s_add_u32 s45, s16, 0x100
	v_mov_b32_e32 v2, 0
	s_addc_u32 s46, s17, 0
	s_mov_b32 s47, -2
	v_mov_b32_e32 v3, v2
	v_mov_b64_e32 v[4:5], v[2:3]
	v_mov_b64_e32 v[6:7], v[2:3]
	v_mov_b64_e32 v[8:9], v[2:3]
	v_mov_b64_e32 v[10:11], v[2:3]
	v_mov_b64_e32 v[12:13], v[2:3]
	v_mov_b64_e32 v[14:15], v[2:3]
	v_mov_b64_e32 v[16:17], v[2:3]
	v_mov_b64_e32 v[18:19], v[2:3]
	v_mov_b64_e32 v[20:21], v[2:3]
	v_mov_b64_e32 v[22:23], v[2:3]
	v_mov_b64_e32 v[24:25], v[2:3]
	v_mov_b64_e32 v[26:27], v[2:3]
	v_mov_b64_e32 v[28:29], v[2:3]
	v_mov_b64_e32 v[30:31], v[2:3]
	v_mov_b64_e32 v[32:33], v[2:3]
	v_mov_b64_e32 v[66:67], v[2:3]
	v_mov_b64_e32 v[68:69], v[2:3]
	v_mov_b64_e32 v[70:71], v[2:3]
	v_mov_b64_e32 v[72:73], v[2:3]
	v_mov_b64_e32 v[74:75], v[2:3]
	v_mov_b64_e32 v[76:77], v[2:3]
	v_mov_b64_e32 v[78:79], v[2:3]
	v_mov_b64_e32 v[80:81], v[2:3]
	v_mov_b64_e32 v[82:83], v[2:3]
	v_mov_b64_e32 v[84:85], v[2:3]
	v_mov_b64_e32 v[86:87], v[2:3]
	v_mov_b64_e32 v[88:89], v[2:3]
	v_mov_b64_e32 v[90:91], v[2:3]
	v_mov_b64_e32 v[92:93], v[2:3]
	v_mov_b64_e32 v[94:95], v[2:3]
	v_mov_b64_e32 v[96:97], v[2:3]
	v_mov_b64_e32 v[34:35], v[2:3]
	v_mov_b64_e32 v[36:37], v[2:3]
	v_mov_b64_e32 v[38:39], v[2:3]
	v_mov_b64_e32 v[40:41], v[2:3]
	v_mov_b64_e32 v[42:43], v[2:3]
	v_mov_b64_e32 v[44:45], v[2:3]
	v_mov_b64_e32 v[46:47], v[2:3]
	v_mov_b64_e32 v[48:49], v[2:3]
	v_mov_b64_e32 v[50:51], v[2:3]
	v_mov_b64_e32 v[52:53], v[2:3]
	v_mov_b64_e32 v[54:55], v[2:3]
	v_mov_b64_e32 v[56:57], v[2:3]
	v_mov_b64_e32 v[58:59], v[2:3]
	v_mov_b64_e32 v[60:61], v[2:3]
	v_mov_b64_e32 v[62:63], v[2:3]
	v_mov_b64_e32 v[64:65], v[2:3]
	v_mov_b64_e32 v[98:99], v[2:3]
	v_mov_b64_e32 v[100:101], v[2:3]
	v_mov_b64_e32 v[102:103], v[2:3]
	v_mov_b64_e32 v[104:105], v[2:3]
	v_mov_b64_e32 v[106:107], v[2:3]
	v_mov_b64_e32 v[108:109], v[2:3]
	v_mov_b64_e32 v[110:111], v[2:3]
	v_mov_b64_e32 v[112:113], v[2:3]
	v_mov_b64_e32 v[114:115], v[2:3]
	v_mov_b64_e32 v[116:117], v[2:3]
	v_mov_b64_e32 v[118:119], v[2:3]
	v_mov_b64_e32 v[120:121], v[2:3]
	v_mov_b64_e32 v[122:123], v[2:3]
	v_mov_b64_e32 v[124:125], v[2:3]
	v_mov_b64_e32 v[126:127], v[2:3]
	v_mov_b64_e32 v[128:129], v[2:3]
	s_cmp_lg_u32 s98, 15
	s_cbranch_scc1 .Lq_unit
